# v68 + P0 outputs stored write-through (sc1) and seam 1 without buffer_wbl2
# speedup vs baseline: 1.0080x; 1.0055x over previous
.LBB0_9:
	s_cmpk_gt_i32 s63, 0x7ff
	s_mov_b64 s[4:5], -1
	s_cbranch_scc0 .LBB0_31
	s_cmpk_gt_u32 s63, 0x9ff
	s_cbranch_scc0 .LBB0_28
	s_cmpk_gt_u32 s63, 0x11ff
	s_cbranch_scc0 .LBB0_13
	s_add_i32 s4, s29, 0xffffdc00
	s_and_b32 s5, s4, 0x3c0
	s_add_i32 s4, s13, 0xfffdc000
	s_and_b32 s4, s4, 0x3e0
	v_or_b32_e32 v4, s5, v1
	s_lshl_b32 s8, s4, 2
	v_lshl_add_u64 v[2:3], v[40:41], 0, s[8:9]
	v_lshlrev_b32_e32 v38, 12, v4
	v_lshl_add_u64 v[30:31], v[2:3], 0, v[38:39]
	v_add_co_u32_e32 v6, vcc, 0x8000, v30
	v_or_b32_e32 v36, s4, v1
	s_nop 0
	v_addc_co_u32_e32 v7, vcc, 0, v31, vcc
	v_add_co_u32_e32 v10, vcc, 0x10000, v30
	global_load_dwordx4 v[2:5], v[30:31], off nt
	s_nop 0
	global_load_dwordx4 v[6:9], v[6:7], off nt
	v_addc_co_u32_e32 v11, vcc, 0, v31, vcc
	v_add_co_u32_e32 v14, vcc, 0x18000, v30
	s_lshl_b32 s8, s5, 1
	s_nop 0
	v_addc_co_u32_e32 v15, vcc, 0, v31, vcc
	v_add_co_u32_e32 v18, vcc, 0x20000, v30
	global_load_dwordx4 v[10:13], v[10:11], off nt
	s_nop 0
	global_load_dwordx4 v[14:17], v[14:15], off nt
	v_addc_co_u32_e32 v19, vcc, 0, v31, vcc
	v_add_co_u32_e32 v22, vcc, 0x28000, v30
	v_lshl_add_u64 v[34:35], v[42:43], 0, s[8:9]
	s_nop 0
	v_addc_co_u32_e32 v23, vcc, 0, v31, vcc
	global_load_dwordx4 v[18:21], v[18:19], off nt
	s_nop 0
	global_load_dwordx4 v[22:25], v[22:23], off nt
	v_add_co_u32_e32 v26, vcc, 0x30000, v30
	v_lshlrev_b32_e32 v38, 11, v36
	s_nop 0
	v_addc_co_u32_e32 v27, vcc, 0, v31, vcc
	global_load_dwordx4 v[26:29], v[26:27], off nt
	v_add_co_u32_e32 v30, vcc, 0x38000, v30
	s_nop 1
	v_addc_co_u32_e32 v31, vcc, 0, v31, vcc
	global_load_dwordx4 v[30:33], v[30:31], off nt
	s_waitcnt vmcnt(7)
	ds_write2_b32 v66, v2, v3 offset1:1
	ds_write2_b32 v66, v4, v5 offset0:2 offset1:3
	s_waitcnt vmcnt(6)
	ds_write2_b32 v67, v6, v7 offset1:1
	ds_write2_b32 v68, v8, v9 offset1:1
	s_waitcnt vmcnt(5)
	ds_write2_b32 v69, v10, v11 offset1:1
	ds_write2_b32 v70, v12, v13 offset1:1
	s_waitcnt vmcnt(4)
	ds_write2_b32 v71, v14, v15 offset1:1
	ds_write2_b32 v72, v16, v17 offset1:1
	s_waitcnt vmcnt(3)
	ds_write2_b32 v73, v18, v19 offset1:1
	ds_write2_b32 v74, v20, v21 offset1:1
	s_waitcnt vmcnt(2)
	ds_write2_b32 v75, v22, v23 offset1:1
	ds_write2_b32 v76, v24, v25 offset1:1
	s_waitcnt vmcnt(1)
	ds_write2_b32 v77, v26, v27 offset1:1
	ds_write2_b32 v78, v28, v29 offset1:1
	s_waitcnt vmcnt(0)
	ds_write2_b32 v79, v30, v31 offset1:1
	ds_write2_b32 v80, v32, v33 offset1:1
	s_waitcnt lgkmcnt(0)
	ds_read2_b32 v[6:7], v63 offset0:33 offset1:41
	ds_read2_b32 v[8:9], v63 offset1:8
	ds_read2_b32 v[10:11], v63 offset0:66 offset1:74
	ds_read2_b32 v[12:13], v63 offset0:99 offset1:107
	ds_read2_b32 v[14:15], v63 offset0:132 offset1:140
	ds_read2_b32 v[16:17], v63 offset0:165 offset1:173
	ds_read2_b32 v[18:19], v63 offset0:198 offset1:206
	ds_read2_b32 v[20:21], v63 offset0:231 offset1:239
	s_waitcnt lgkmcnt(6)
	v_bfe_u32 v2, v8, 16, 1
	v_bfe_u32 v3, v6, 16, 1
	s_waitcnt lgkmcnt(5)
	v_bfe_u32 v4, v10, 16, 1
	s_waitcnt lgkmcnt(3)
	v_bfe_u32 v22, v14, 16, 1
	s_waitcnt lgkmcnt(1)
	v_bfe_u32 v24, v18, 16, 1
	v_bfe_u32 v5, v12, 16, 1
	v_bfe_u32 v23, v16, 16, 1
	s_waitcnt lgkmcnt(0)
	v_bfe_u32 v25, v20, 16, 1
	v_add3_u32 v2, v8, v2, s45
	v_add3_u32 v3, v6, v3, s45
	v_add3_u32 v4, v10, v4, s45
	v_add3_u32 v6, v14, v22, s45
	v_add3_u32 v10, v18, v24, s45
	v_add3_u32 v5, v12, v5, s45
	v_add3_u32 v8, v16, v23, s45
	v_add3_u32 v12, v20, v25, s45
	v_lshrrev_b32_e32 v2, 16, v2
	v_lshrrev_b32_e32 v4, 16, v4
	v_lshrrev_b32_e32 v6, 16, v6
	v_lshrrev_b32_e32 v10, 16, v10
	v_and_or_b32 v2, v3, s56, v2
	v_and_or_b32 v3, v5, s56, v4
	v_and_or_b32 v4, v8, s56, v6
	v_and_or_b32 v5, v12, s56, v10
	v_lshl_add_u64 v[22:23], v[34:35], 0, v[38:39]
	global_store_dwordx4 v[22:23], v[2:5], off sc1
	v_bfe_u32 v6, v21, 16, 1
	v_or_b32_e32 v8, s4, v60
	v_bfe_u32 v2, v9, 16, 1
	v_add3_u32 v2, v9, v2, s45
	v_bfe_u32 v3, v7, 16, 1
	v_lshrrev_b32_e32 v2, 16, v2
	v_add3_u32 v3, v7, v3, s45
	v_and_or_b32 v2, v3, s56, v2
	v_bfe_u32 v3, v11, 16, 1
	v_add3_u32 v3, v11, v3, s45
	v_bfe_u32 v4, v13, 16, 1
	v_lshrrev_b32_e32 v3, 16, v3
	v_add3_u32 v4, v13, v4, s45
	v_and_or_b32 v3, v4, s56, v3
	v_bfe_u32 v4, v15, 16, 1
	v_add3_u32 v4, v15, v4, s45
	v_bfe_u32 v5, v17, 16, 1
	v_lshrrev_b32_e32 v4, 16, v4
	v_add3_u32 v5, v17, v5, s45
	v_and_or_b32 v4, v5, s56, v4
	v_bfe_u32 v5, v19, 16, 1
	v_add3_u32 v5, v19, v5, s45
	v_lshrrev_b32_e32 v5, 16, v5
	v_add3_u32 v6, v21, v6, s45
	v_lshlrev_b32_e32 v38, 11, v8
	v_and_or_b32 v5, v6, s56, v5
	ds_read2_b32 v[6:7], v63 offset0:16 offset1:24
	v_lshl_add_u64 v[8:9], v[34:35], 0, v[38:39]
	global_store_dwordx4 v[8:9], v[2:5], off sc1
	ds_read2_b32 v[8:9], v63 offset0:49 offset1:57
	ds_read2_b32 v[10:11], v63 offset0:82 offset1:90
	ds_read2_b32 v[12:13], v63 offset0:115 offset1:123
	s_waitcnt lgkmcnt(3)
	v_bfe_u32 v2, v6, 16, 1
	v_add3_u32 v2, v6, v2, s45
	s_waitcnt lgkmcnt(2)
	v_bfe_u32 v3, v8, 16, 1
	ds_read2_b32 v[14:15], v63 offset0:148 offset1:156
	v_lshrrev_b32_e32 v2, 16, v2
	v_add3_u32 v3, v8, v3, s45
	ds_read2_b32 v[16:17], v63 offset0:181 offset1:189
	v_and_or_b32 v2, v3, s56, v2
	s_waitcnt lgkmcnt(3)
	v_bfe_u32 v3, v10, 16, 1
	v_add3_u32 v3, v10, v3, s45
	s_waitcnt lgkmcnt(2)
	v_bfe_u32 v4, v12, 16, 1
	ds_read2_b32 v[18:19], v63 offset0:214 offset1:222
	v_lshrrev_b32_e32 v3, 16, v3
	v_add3_u32 v4, v12, v4, s45
	ds_read2_b32 v[20:21], v63 offset0:247 offset1:255
	v_and_or_b32 v3, v4, s56, v3
	s_waitcnt lgkmcnt(3)
	v_bfe_u32 v4, v14, 16, 1
	v_add3_u32 v4, v14, v4, s45
	s_waitcnt lgkmcnt(2)
	v_bfe_u32 v5, v16, 16, 1
	v_lshrrev_b32_e32 v4, 16, v4
	v_add3_u32 v5, v16, v5, s45
	v_and_or_b32 v4, v5, s56, v4
	s_waitcnt lgkmcnt(1)
	v_bfe_u32 v5, v18, 16, 1
	v_add3_u32 v5, v18, v5, s45
	s_waitcnt lgkmcnt(0)
	v_bfe_u32 v6, v20, 16, 1
	v_lshrrev_b32_e32 v5, 16, v5
	v_add3_u32 v6, v20, v6, s45
	v_and_or_b32 v5, v6, s56, v5
	v_or_b32_e32 v6, s4, v61
	v_lshlrev_b32_e32 v38, 11, v6
	v_lshl_add_u64 v[22:23], v[34:35], 0, v[38:39]
	global_store_dwordx4 v[22:23], v[2:5], off sc1
	v_bfe_u32 v6, v21, 16, 1
	v_add3_u32 v6, v21, v6, s45
	v_bfe_u32 v2, v7, 16, 1
	v_add3_u32 v2, v7, v2, s45
	v_bfe_u32 v3, v9, 16, 1
	v_lshrrev_b32_e32 v2, 16, v2
	v_add3_u32 v3, v9, v3, s45
	v_and_or_b32 v2, v3, s56, v2
	v_bfe_u32 v3, v11, 16, 1
	v_add3_u32 v3, v11, v3, s45
	v_bfe_u32 v4, v13, 16, 1
	v_lshrrev_b32_e32 v3, 16, v3
	v_add3_u32 v4, v13, v4, s45
	v_and_or_b32 v3, v4, s56, v3
	v_bfe_u32 v4, v15, 16, 1
	v_add3_u32 v4, v15, v4, s45
	v_bfe_u32 v5, v17, 16, 1
	v_lshrrev_b32_e32 v4, 16, v4
	v_add3_u32 v5, v17, v5, s45
	v_and_or_b32 v4, v5, s56, v4
	v_bfe_u32 v5, v19, 16, 1
	v_add3_u32 v5, v19, v5, s45
	v_lshrrev_b32_e32 v5, 16, v5
	v_and_or_b32 v5, v6, s56, v5
	v_or_b32_e32 v6, s4, v62
	v_lshlrev_b32_e32 v38, 11, v6
	v_lshl_add_u64 v[6:7], v[34:35], 0, v[38:39]
	global_store_dwordx4 v[6:7], v[2:5], off sc1
	s_waitcnt lgkmcnt(0)
	s_mov_b64 s[4:5], 0

.LBB0_26:
	s_waitcnt vmcnt(1)
	v_add_u32_e32 v2, 0x840, v81
	ds_write2_b32 v2, v16, v17 offset1:1
	v_add_u32_e32 v2, 0x848, v81
	ds_write2_b32 v2, v14, v15 offset1:1
	v_add_u32_e32 v2, 0xc60, v81
	ds_write2_b32 v2, v10, v11 offset1:1
	v_add_u32_e32 v2, 0xc68, v81
	ds_write2_b32 v2, v12, v13 offset1:1
	s_waitcnt lgkmcnt(0)
	s_waitcnt vmcnt(0)
	ds_read2_b32 v[6:7], v63 offset1:8
	ds_read2_b32 v[10:11], v63 offset0:33 offset1:41
	ds_read2_b32 v[12:13], v63 offset0:66 offset1:74
	ds_read2_b32 v[14:15], v63 offset0:99 offset1:107
	ds_read2_b32 v[16:17], v63 offset0:132 offset1:140
	s_waitcnt lgkmcnt(4)
	v_bfe_u32 v2, v6, 16, 1
	v_add3_u32 v2, v6, v2, s45
	s_waitcnt lgkmcnt(3)
	v_bfe_u32 v3, v10, 16, 1
	v_lshrrev_b32_e32 v2, 16, v2
	v_add3_u32 v3, v10, v3, s45
	ds_read2_b32 v[18:19], v63 offset0:165 offset1:173
	v_and_or_b32 v2, v3, s56, v2
	s_waitcnt lgkmcnt(3)
	v_bfe_u32 v3, v12, 16, 1
	v_add3_u32 v3, v12, v3, s45
	s_waitcnt lgkmcnt(2)
	v_bfe_u32 v4, v14, 16, 1
	ds_read2_b32 v[20:21], v63 offset0:198 offset1:206
	v_lshrrev_b32_e32 v3, 16, v3
	v_add3_u32 v4, v14, v4, s45
	ds_read2_b32 v[22:23], v63 offset0:231 offset1:239
	v_and_or_b32 v3, v4, s56, v3
	s_waitcnt lgkmcnt(3)
	v_bfe_u32 v4, v16, 16, 1
	v_add3_u32 v4, v16, v4, s45
	s_waitcnt lgkmcnt(2)
	v_bfe_u32 v5, v18, 16, 1
	s_add_i32 s4, s21, 0xfffb0000
	v_lshrrev_b32_e32 v4, 16, v4
	v_add3_u32 v5, v18, v5, s45
	s_and_b32 s4, s4, 0x80
	s_and_b32 s8, s15, 0xf00
	v_and_or_b32 v4, v5, s56, v4
	s_waitcnt lgkmcnt(1)
	v_bfe_u32 v5, v20, 16, 1
	s_and_b32 s5, s41, 0x60
	s_or_b32 s4, s8, s4
	v_add3_u32 v5, v20, v5, s45
	s_waitcnt lgkmcnt(0)
	v_bfe_u32 v6, v22, 16, 1
	s_or_b32 s4, s4, s5
	v_lshrrev_b32_e32 v5, 16, v5
	v_add3_u32 v6, v22, v6, s45
	s_lshl_b32 s8, s14, 1
	v_and_or_b32 v5, v6, s56, v5
	v_or_b32_e32 v6, s4, v1
	v_lshl_add_u64 v[8:9], v[46:47], 0, s[8:9]
	v_lshlrev_b32_e32 v38, 11, v6
	v_lshl_add_u64 v[24:25], v[8:9], 0, v[38:39]
	global_store_dwordx4 v[24:25], v[2:5], off sc1
	v_bfe_u32 v6, v23, 16, 1
	v_or_b32_e32 v10, s4, v60
	v_bfe_u32 v2, v7, 16, 1
	v_add3_u32 v2, v7, v2, s45
	v_bfe_u32 v3, v11, 16, 1
	v_lshrrev_b32_e32 v2, 16, v2
	v_add3_u32 v3, v11, v3, s45
	v_and_or_b32 v2, v3, s56, v2
	v_bfe_u32 v3, v13, 16, 1
	v_add3_u32 v3, v13, v3, s45
	v_bfe_u32 v4, v15, 16, 1
	v_lshrrev_b32_e32 v3, 16, v3
	v_add3_u32 v4, v15, v4, s45
	v_and_or_b32 v3, v4, s56, v3
	v_bfe_u32 v4, v17, 16, 1
	v_add3_u32 v4, v17, v4, s45
	v_bfe_u32 v5, v19, 16, 1
	v_lshrrev_b32_e32 v4, 16, v4
	v_add3_u32 v5, v19, v5, s45
	v_and_or_b32 v4, v5, s56, v4
	v_bfe_u32 v5, v21, 16, 1
	v_add3_u32 v5, v21, v5, s45
	v_lshrrev_b32_e32 v5, 16, v5
	v_add3_u32 v6, v23, v6, s45
	v_lshlrev_b32_e32 v38, 11, v10
	v_and_or_b32 v5, v6, s56, v5
	ds_read2_b32 v[6:7], v63 offset0:16 offset1:24
	v_lshl_add_u64 v[10:11], v[8:9], 0, v[38:39]
	global_store_dwordx4 v[10:11], v[2:5], off sc1
	ds_read2_b32 v[10:11], v63 offset0:49 offset1:57
	ds_read2_b32 v[12:13], v63 offset0:82 offset1:90
	ds_read2_b32 v[14:15], v63 offset0:115 offset1:123
	s_waitcnt lgkmcnt(3)
	v_bfe_u32 v2, v6, 16, 1
	v_add3_u32 v2, v6, v2, s45
	s_waitcnt lgkmcnt(2)
	v_bfe_u32 v3, v10, 16, 1
	ds_read2_b32 v[16:17], v63 offset0:148 offset1:156
	v_lshrrev_b32_e32 v2, 16, v2
	v_add3_u32 v3, v10, v3, s45
	ds_read2_b32 v[18:19], v63 offset0:181 offset1:189
	v_and_or_b32 v2, v3, s56, v2
	s_waitcnt lgkmcnt(3)
	v_bfe_u32 v3, v12, 16, 1
	v_add3_u32 v3, v12, v3, s45
	s_waitcnt lgkmcnt(2)
	v_bfe_u32 v4, v14, 16, 1
	ds_read2_b32 v[20:21], v63 offset0:214 offset1:222
	v_lshrrev_b32_e32 v3, 16, v3
	v_add3_u32 v4, v14, v4, s45
	ds_read2_b32 v[22:23], v63 offset0:247 offset1:255
	v_and_or_b32 v3, v4, s56, v3
	s_waitcnt lgkmcnt(3)
	v_bfe_u32 v4, v16, 16, 1
	v_add3_u32 v4, v16, v4, s45
	s_waitcnt lgkmcnt(2)
	v_bfe_u32 v5, v18, 16, 1
	v_lshrrev_b32_e32 v4, 16, v4
	v_add3_u32 v5, v18, v5, s45
	v_and_or_b32 v4, v5, s56, v4
	s_waitcnt lgkmcnt(1)
	v_bfe_u32 v5, v20, 16, 1
	v_add3_u32 v5, v20, v5, s45
	s_waitcnt lgkmcnt(0)
	v_bfe_u32 v6, v22, 16, 1
	v_lshrrev_b32_e32 v5, 16, v5
	v_add3_u32 v6, v22, v6, s45
	v_and_or_b32 v5, v6, s56, v5
	v_or_b32_e32 v6, s4, v61
	v_lshlrev_b32_e32 v38, 11, v6
	v_lshl_add_u64 v[24:25], v[8:9], 0, v[38:39]
	global_store_dwordx4 v[24:25], v[2:5], off sc1
	v_bfe_u32 v6, v23, 16, 1
	v_add3_u32 v6, v23, v6, s45
	v_bfe_u32 v2, v7, 16, 1
	v_add3_u32 v2, v7, v2, s45
	v_bfe_u32 v3, v11, 16, 1
	v_lshrrev_b32_e32 v2, 16, v2
	v_add3_u32 v3, v11, v3, s45
	v_and_or_b32 v2, v3, s56, v2
	v_bfe_u32 v3, v13, 16, 1
	v_add3_u32 v3, v13, v3, s45
	v_bfe_u32 v4, v15, 16, 1
	v_lshrrev_b32_e32 v3, 16, v3
	v_add3_u32 v4, v15, v4, s45
	v_and_or_b32 v3, v4, s56, v3
	v_bfe_u32 v4, v17, 16, 1
	v_add3_u32 v4, v17, v4, s45
	v_bfe_u32 v5, v19, 16, 1
	v_lshrrev_b32_e32 v4, 16, v4
	v_add3_u32 v5, v19, v5, s45
	v_and_or_b32 v4, v5, s56, v4
	v_bfe_u32 v5, v21, 16, 1
	v_add3_u32 v5, v21, v5, s45
	v_lshrrev_b32_e32 v5, 16, v5
	v_and_or_b32 v5, v6, s56, v5
	v_or_b32_e32 v6, s4, v62
	v_lshlrev_b32_e32 v38, 11, v6
	v_lshl_add_u64 v[6:7], v[8:9], 0, v[38:39]
	global_store_dwordx4 v[6:7], v[2:5], off sc1
	s_waitcnt lgkmcnt(0)

.LBB0_28:
	s_andn2_b64 vcc, exec, s[4:5]
	s_cbranch_vccnz .LBB0_30
	s_add_i32 s4, s29, 0xfffff000
	s_and_b32 s5, s4, 0x3c0
	s_add_i32 s4, s13, 0xffff0000
	s_and_b32 s4, s4, 0x3e0
	v_or_b32_e32 v4, s5, v1
	s_lshl_b32 s8, s4, 2
	v_lshl_add_u64 v[2:3], v[48:49], 0, s[8:9]
	v_lshlrev_b32_e32 v38, 12, v4
	v_lshl_add_u64 v[30:31], v[2:3], 0, v[38:39]
	v_add_co_u32_e32 v6, vcc, 0x8000, v30
	v_or_b32_e32 v36, s4, v1
	s_nop 0
	v_addc_co_u32_e32 v7, vcc, 0, v31, vcc
	v_add_co_u32_e32 v10, vcc, 0x10000, v30
	global_load_dwordx4 v[2:5], v[30:31], off nt
	s_nop 0
	global_load_dwordx4 v[6:9], v[6:7], off nt
	v_addc_co_u32_e32 v11, vcc, 0, v31, vcc
	v_add_co_u32_e32 v14, vcc, 0x18000, v30
	s_lshl_b32 s8, s5, 1
	s_nop 0
	v_addc_co_u32_e32 v15, vcc, 0, v31, vcc
	v_add_co_u32_e32 v18, vcc, 0x20000, v30
	global_load_dwordx4 v[10:13], v[10:11], off nt
	s_nop 0
	global_load_dwordx4 v[14:17], v[14:15], off nt
	v_addc_co_u32_e32 v19, vcc, 0, v31, vcc
	v_add_co_u32_e32 v22, vcc, 0x28000, v30
	v_lshl_add_u64 v[34:35], v[50:51], 0, s[8:9]
	s_nop 0
	v_addc_co_u32_e32 v23, vcc, 0, v31, vcc
	global_load_dwordx4 v[18:21], v[18:19], off nt
	s_nop 0
	global_load_dwordx4 v[22:25], v[22:23], off nt
	v_add_co_u32_e32 v26, vcc, 0x30000, v30
	v_lshlrev_b32_e32 v38, 11, v36
	s_nop 0
	v_addc_co_u32_e32 v27, vcc, 0, v31, vcc
	global_load_dwordx4 v[26:29], v[26:27], off nt
	v_add_co_u32_e32 v30, vcc, 0x38000, v30
	s_nop 1
	v_addc_co_u32_e32 v31, vcc, 0, v31, vcc
	global_load_dwordx4 v[30:33], v[30:31], off nt
	s_waitcnt vmcnt(7)
	ds_write2_b32 v66, v2, v3 offset1:1
	ds_write2_b32 v66, v4, v5 offset0:2 offset1:3
	s_waitcnt vmcnt(6)
	ds_write2_b32 v67, v6, v7 offset1:1
	ds_write2_b32 v68, v8, v9 offset1:1
	s_waitcnt vmcnt(5)
	ds_write2_b32 v69, v10, v11 offset1:1
	ds_write2_b32 v70, v12, v13 offset1:1
	s_waitcnt vmcnt(4)
	ds_write2_b32 v71, v14, v15 offset1:1
	ds_write2_b32 v72, v16, v17 offset1:1
	s_waitcnt vmcnt(3)
	ds_write2_b32 v73, v18, v19 offset1:1
	ds_write2_b32 v74, v20, v21 offset1:1
	s_waitcnt vmcnt(2)
	ds_write2_b32 v75, v22, v23 offset1:1
	ds_write2_b32 v76, v24, v25 offset1:1
	s_waitcnt vmcnt(1)
	ds_write2_b32 v77, v26, v27 offset1:1
	ds_write2_b32 v78, v28, v29 offset1:1
	s_waitcnt vmcnt(0)
	ds_write2_b32 v79, v30, v31 offset1:1
	ds_write2_b32 v80, v32, v33 offset1:1
	s_waitcnt lgkmcnt(0)
	ds_read2_b32 v[6:7], v63 offset0:33 offset1:41
	ds_read2_b32 v[8:9], v63 offset1:8
	ds_read2_b32 v[10:11], v63 offset0:66 offset1:74
	ds_read2_b32 v[12:13], v63 offset0:99 offset1:107
	ds_read2_b32 v[14:15], v63 offset0:132 offset1:140
	ds_read2_b32 v[16:17], v63 offset0:165 offset1:173
	ds_read2_b32 v[18:19], v63 offset0:198 offset1:206
	ds_read2_b32 v[20:21], v63 offset0:231 offset1:239
	s_waitcnt lgkmcnt(6)
	v_bfe_u32 v2, v8, 16, 1
	v_bfe_u32 v3, v6, 16, 1
	s_waitcnt lgkmcnt(5)
	v_bfe_u32 v4, v10, 16, 1
	s_waitcnt lgkmcnt(3)
	v_bfe_u32 v22, v14, 16, 1
	s_waitcnt lgkmcnt(1)
	v_bfe_u32 v24, v18, 16, 1
	v_bfe_u32 v5, v12, 16, 1
	v_bfe_u32 v23, v16, 16, 1
	s_waitcnt lgkmcnt(0)
	v_bfe_u32 v25, v20, 16, 1
	v_add3_u32 v2, v8, v2, s45
	v_add3_u32 v3, v6, v3, s45
	v_add3_u32 v4, v10, v4, s45
	v_add3_u32 v6, v14, v22, s45
	v_add3_u32 v10, v18, v24, s45
	v_add3_u32 v5, v12, v5, s45
	v_add3_u32 v8, v16, v23, s45
	v_add3_u32 v12, v20, v25, s45
	v_lshrrev_b32_e32 v2, 16, v2
	v_lshrrev_b32_e32 v4, 16, v4
	v_lshrrev_b32_e32 v6, 16, v6
	v_lshrrev_b32_e32 v10, 16, v10
	v_and_or_b32 v2, v3, s56, v2
	v_and_or_b32 v3, v5, s56, v4
	v_and_or_b32 v4, v8, s56, v6
	v_and_or_b32 v5, v12, s56, v10
	v_lshl_add_u64 v[22:23], v[34:35], 0, v[38:39]
	global_store_dwordx4 v[22:23], v[2:5], off sc1
	v_bfe_u32 v6, v21, 16, 1
	v_or_b32_e32 v8, s4, v60
	v_bfe_u32 v2, v9, 16, 1
	v_add3_u32 v2, v9, v2, s45
	v_bfe_u32 v3, v7, 16, 1
	v_lshrrev_b32_e32 v2, 16, v2
	v_add3_u32 v3, v7, v3, s45
	v_and_or_b32 v2, v3, s56, v2
	v_bfe_u32 v3, v11, 16, 1
	v_add3_u32 v3, v11, v3, s45
	v_bfe_u32 v4, v13, 16, 1
	v_lshrrev_b32_e32 v3, 16, v3
	v_add3_u32 v4, v13, v4, s45
	v_and_or_b32 v3, v4, s56, v3
	v_bfe_u32 v4, v15, 16, 1
	v_add3_u32 v4, v15, v4, s45
	v_bfe_u32 v5, v17, 16, 1
	v_lshrrev_b32_e32 v4, 16, v4
	v_add3_u32 v5, v17, v5, s45
	v_and_or_b32 v4, v5, s56, v4
	v_bfe_u32 v5, v19, 16, 1
	v_add3_u32 v5, v19, v5, s45
	v_lshrrev_b32_e32 v5, 16, v5
	v_add3_u32 v6, v21, v6, s45
	v_lshlrev_b32_e32 v38, 11, v8
	v_and_or_b32 v5, v6, s56, v5
	ds_read2_b32 v[6:7], v63 offset0:16 offset1:24
	v_lshl_add_u64 v[8:9], v[34:35], 0, v[38:39]
	global_store_dwordx4 v[8:9], v[2:5], off sc1
	ds_read2_b32 v[8:9], v63 offset0:49 offset1:57
	ds_read2_b32 v[10:11], v63 offset0:82 offset1:90
	ds_read2_b32 v[12:13], v63 offset0:115 offset1:123
	s_waitcnt lgkmcnt(3)
	v_bfe_u32 v2, v6, 16, 1
	v_add3_u32 v2, v6, v2, s45
	s_waitcnt lgkmcnt(2)
	v_bfe_u32 v3, v8, 16, 1
	ds_read2_b32 v[14:15], v63 offset0:148 offset1:156
	v_lshrrev_b32_e32 v2, 16, v2
	v_add3_u32 v3, v8, v3, s45
	ds_read2_b32 v[16:17], v63 offset0:181 offset1:189
	v_and_or_b32 v2, v3, s56, v2
	s_waitcnt lgkmcnt(3)
	v_bfe_u32 v3, v10, 16, 1
	v_add3_u32 v3, v10, v3, s45
	s_waitcnt lgkmcnt(2)
	v_bfe_u32 v4, v12, 16, 1
	ds_read2_b32 v[18:19], v63 offset0:214 offset1:222
	v_lshrrev_b32_e32 v3, 16, v3
	v_add3_u32 v4, v12, v4, s45
	ds_read2_b32 v[20:21], v63 offset0:247 offset1:255
	v_and_or_b32 v3, v4, s56, v3
	s_waitcnt lgkmcnt(3)
	v_bfe_u32 v4, v14, 16, 1
	v_add3_u32 v4, v14, v4, s45
	s_waitcnt lgkmcnt(2)
	v_bfe_u32 v5, v16, 16, 1
	v_lshrrev_b32_e32 v4, 16, v4
	v_add3_u32 v5, v16, v5, s45
	v_and_or_b32 v4, v5, s56, v4
	s_waitcnt lgkmcnt(1)
	v_bfe_u32 v5, v18, 16, 1
	v_add3_u32 v5, v18, v5, s45
	s_waitcnt lgkmcnt(0)
	v_bfe_u32 v6, v20, 16, 1
	v_lshrrev_b32_e32 v5, 16, v5
	v_add3_u32 v6, v20, v6, s45
	v_and_or_b32 v5, v6, s56, v5
	v_or_b32_e32 v6, s4, v61
	v_lshlrev_b32_e32 v38, 11, v6
	v_lshl_add_u64 v[22:23], v[34:35], 0, v[38:39]
	global_store_dwordx4 v[22:23], v[2:5], off sc1
	v_bfe_u32 v6, v21, 16, 1
	v_add3_u32 v6, v21, v6, s45
	v_bfe_u32 v2, v7, 16, 1
	v_add3_u32 v2, v7, v2, s45
	v_bfe_u32 v3, v9, 16, 1
	v_lshrrev_b32_e32 v2, 16, v2
	v_add3_u32 v3, v9, v3, s45
	v_and_or_b32 v2, v3, s56, v2
	v_bfe_u32 v3, v11, 16, 1
	v_add3_u32 v3, v11, v3, s45
	v_bfe_u32 v4, v13, 16, 1
	v_lshrrev_b32_e32 v3, 16, v3
	v_add3_u32 v4, v13, v4, s45
	v_and_or_b32 v3, v4, s56, v3
	v_bfe_u32 v4, v15, 16, 1
	v_add3_u32 v4, v15, v4, s45
	v_bfe_u32 v5, v17, 16, 1
	v_lshrrev_b32_e32 v4, 16, v4
	v_add3_u32 v5, v17, v5, s45
	v_and_or_b32 v4, v5, s56, v4
	v_bfe_u32 v5, v19, 16, 1
	v_add3_u32 v5, v19, v5, s45
	v_lshrrev_b32_e32 v5, 16, v5
	v_and_or_b32 v5, v6, s56, v5
	v_or_b32_e32 v6, s4, v62
	v_lshlrev_b32_e32 v38, 11, v6
	v_lshl_add_u64 v[6:7], v[34:35], 0, v[38:39]
	global_store_dwordx4 v[6:7], v[2:5], off sc1
	s_waitcnt lgkmcnt(0)

.LBB0_31:
	s_andn2_b64 vcc, exec, s[4:5]
	s_cbranch_vccnz .LBB0_8
	s_ashr_i32 s4, s63, 31
	s_lshr_b32 s4, s4, 25
	s_add_i32 s4, s63, s4
	s_ashr_i32 s8, s4, 7
	s_lshl_b32 s4, s8, 6
	s_lshl_b32 s5, s8, 12
	v_or_b32_e32 v30, s4, v1
	s_sub_i32 s14, s13, s5
	v_or_b32_e32 v4, 8, v30
	v_or_b32_e32 v10, 16, v30
	v_or_b32_e32 v12, 24, v30
	v_or_b32_e32 v18, 32, v30
	v_or_b32_e32 v20, 40, v30
	s_ashr_i32 s15, s14, 31
	v_ashrrev_i32_e32 v31, 31, v30
	v_ashrrev_i32_e32 v5, 31, v4
	v_ashrrev_i32_e32 v11, 31, v10
	v_ashrrev_i32_e32 v13, 31, v12
	v_ashrrev_i32_e32 v19, 31, v18
	v_ashrrev_i32_e32 v21, 31, v20
	v_lshl_add_u64 v[32:33], s[14:15], 2, v[52:53]
	v_lshlrev_b64 v[2:3], 14, v[30:31]
	v_lshlrev_b64 v[4:5], 14, v[4:5]
	v_lshlrev_b64 v[10:11], 14, v[10:11]
	v_lshlrev_b64 v[12:13], 14, v[12:13]
	v_lshlrev_b64 v[18:19], 14, v[18:19]
	v_lshlrev_b64 v[20:21], 14, v[20:21]
	v_lshl_add_u64 v[2:3], v[32:33], 0, v[2:3]
	v_lshl_add_u64 v[6:7], v[32:33], 0, v[4:5]
	v_lshl_add_u64 v[10:11], v[32:33], 0, v[10:11]
	v_lshl_add_u64 v[14:15], v[32:33], 0, v[12:13]
	v_lshl_add_u64 v[18:19], v[32:33], 0, v[18:19]
	v_lshl_add_u64 v[22:23], v[32:33], 0, v[20:21]
	global_load_dwordx4 v[2:5], v[2:3], off nt
	s_nop 0
	global_load_dwordx4 v[6:9], v[6:7], off nt
	s_nop 0
	global_load_dwordx4 v[10:13], v[10:11], off nt
	s_nop 0
	global_load_dwordx4 v[14:17], v[14:15], off nt
	s_nop 0
	global_load_dwordx4 v[18:21], v[18:19], off nt
	s_nop 0
	global_load_dwordx4 v[22:25], v[22:23], off nt
	v_or_b32_e32 v26, 48, v30
	v_ashrrev_i32_e32 v27, 31, v26
	v_lshlrev_b64 v[26:27], 14, v[26:27]
	v_or_b32_e32 v30, 56, v30
	v_lshl_add_u64 v[26:27], v[32:33], 0, v[26:27]
	v_ashrrev_i32_e32 v31, 31, v30
	global_load_dwordx4 v[26:29], v[26:27], off nt
	v_lshlrev_b64 v[30:31], 14, v[30:31]
	v_lshl_add_u64 v[30:31], v[32:33], 0, v[30:31]
	global_load_dwordx4 v[30:33], v[30:31], off nt
	s_lshl_b32 s15, s8, 8
	s_sub_i32 s18, s21, s5
	s_sub_i32 s15, s29, s15
	s_ashr_i32 s5, s4, 31
	s_and_b32 s18, s18, 0xf00
	s_and_b32 s15, s15, 0xffffff80
	s_lshr_b32 s14, s14, 8
	v_lshl_add_u64 v[34:35], s[4:5], 1, v[54:55]
	s_add_i32 s18, s18, s15
	s_and_b32 s4, s14, 4
	s_or_b32 s4, s18, s4
	v_or_b32_e32 v36, s4, v64
	s_lshl_b32 s4, s8, 13
	s_waitcnt vmcnt(7)
	ds_write2_b32 v66, v2, v3 offset1:1
	ds_write2_b32 v66, v4, v5 offset0:2 offset1:3
	s_waitcnt vmcnt(6)
	ds_write2_b32 v67, v6, v7 offset1:1
	ds_write2_b32 v68, v8, v9 offset1:1
	s_waitcnt vmcnt(5)
	ds_write2_b32 v69, v10, v11 offset1:1
	ds_write2_b32 v70, v12, v13 offset1:1
	s_waitcnt vmcnt(4)
	ds_write2_b32 v71, v14, v15 offset1:1
	ds_write2_b32 v72, v16, v17 offset1:1
	s_waitcnt vmcnt(3)
	ds_write2_b32 v73, v18, v19 offset1:1
	ds_write2_b32 v74, v20, v21 offset1:1
	s_waitcnt vmcnt(2)
	ds_write2_b32 v75, v22, v23 offset1:1
	ds_write2_b32 v76, v24, v25 offset1:1
	s_waitcnt vmcnt(1)
	ds_write2_b32 v77, v26, v27 offset1:1
	ds_write2_b32 v78, v28, v29 offset1:1
	s_waitcnt vmcnt(0)
	ds_write2_b32 v79, v30, v31 offset1:1
	ds_write2_b32 v80, v32, v33 offset1:1
	s_waitcnt lgkmcnt(0)
	ds_read2_b32 v[6:7], v63 offset0:33 offset1:41
	ds_read2_b32 v[8:9], v63 offset1:8
	ds_read2_b32 v[10:11], v63 offset0:66 offset1:74
	ds_read2_b32 v[12:13], v63 offset0:99 offset1:107
	ds_read2_b32 v[14:15], v63 offset0:132 offset1:140
	ds_read2_b32 v[16:17], v63 offset0:165 offset1:173
	ds_read2_b32 v[18:19], v63 offset0:198 offset1:206
	s_waitcnt lgkmcnt(5)
	v_bfe_u32 v2, v8, 16, 1
	s_waitcnt lgkmcnt(4)
	v_bfe_u32 v4, v10, 16, 1
	v_bfe_u32 v3, v6, 16, 1
	s_waitcnt lgkmcnt(3)
	v_bfe_u32 v5, v12, 16, 1
	v_add3_u32 v2, v8, v2, s45
	v_add3_u32 v4, v10, v4, s45
	s_waitcnt lgkmcnt(2)
	v_bfe_u32 v20, v14, 16, 1
	s_waitcnt lgkmcnt(1)
	v_bfe_u32 v21, v16, 16, 1
	v_add3_u32 v3, v6, v3, s45
	v_add3_u32 v5, v12, v5, s45
	v_lshrrev_b32_e32 v2, 16, v2
	v_lshrrev_b32_e32 v4, 16, v4
	v_add3_u32 v6, v14, v20, s45
	v_and_or_b32 v2, v3, s56, v2
	v_and_or_b32 v3, v5, s56, v4
	v_add3_u32 v4, v16, v21, s45
	ds_read2_b32 v[20:21], v63 offset0:231 offset1:239
	v_subrev_u32_e32 v24, s4, v65
	v_lshrrev_b32_e32 v6, 16, v6
	s_waitcnt lgkmcnt(1)
	v_bfe_u32 v5, v18, 16, 1
	v_and_or_b32 v22, v24, s57, v36
	v_and_or_b32 v4, v4, s56, v6
	v_add3_u32 v5, v18, v5, s45
	s_waitcnt lgkmcnt(0)
	v_bfe_u32 v6, v20, 16, 1
	v_ashrrev_i32_e32 v23, 31, v22
	v_lshrrev_b32_e32 v5, 16, v5
	v_add3_u32 v6, v20, v6, s45
	v_lshlrev_b64 v[22:23], 11, v[22:23]
	v_and_or_b32 v5, v6, s56, v5
	v_lshl_add_u64 v[22:23], v[34:35], 0, v[22:23]
	global_store_dwordx4 v[22:23], v[2:5], off sc1
	v_bfe_u32 v6, v21, 16, 1
	v_add3_u32 v6, v21, v6, s45
	v_bfe_u32 v2, v9, 16, 1
	v_add3_u32 v2, v9, v2, s45
	v_bfe_u32 v3, v7, 16, 1
	v_lshrrev_b32_e32 v2, 16, v2
	v_add3_u32 v3, v7, v3, s45
	v_and_or_b32 v2, v3, s56, v2
	v_bfe_u32 v3, v11, 16, 1
	v_add3_u32 v3, v11, v3, s45
	v_bfe_u32 v4, v13, 16, 1
	v_lshrrev_b32_e32 v3, 16, v3
	v_add3_u32 v4, v13, v4, s45
	v_and_or_b32 v3, v4, s56, v3
	v_bfe_u32 v4, v15, 16, 1
	v_add3_u32 v4, v15, v4, s45
	v_bfe_u32 v5, v17, 16, 1
	v_lshrrev_b32_e32 v4, 16, v4
	v_add3_u32 v5, v17, v5, s45
	v_and_or_b32 v4, v5, s56, v4
	v_bfe_u32 v5, v19, 16, 1
	v_add3_u32 v5, v19, v5, s45
	v_lshrrev_b32_e32 v5, 16, v5
	v_and_or_b32 v5, v6, s56, v5
	v_add_u32_e32 v6, 16, v24
	v_and_or_b32 v6, v6, s60, v36
	v_ashrrev_i32_e32 v7, 31, v6
	v_lshlrev_b64 v[6:7], 11, v[6:7]
	ds_read2_b32 v[8:9], v63 offset0:16 offset1:24
	v_lshl_add_u64 v[6:7], v[34:35], 0, v[6:7]
	global_store_dwordx4 v[6:7], v[2:5], off sc1
	ds_read2_b32 v[6:7], v63 offset0:49 offset1:57
	ds_read2_b32 v[10:11], v63 offset0:82 offset1:90
	ds_read2_b32 v[12:13], v63 offset0:115 offset1:123
	s_waitcnt lgkmcnt(3)
	v_bfe_u32 v2, v8, 16, 1
	v_add3_u32 v2, v8, v2, s45
	s_waitcnt lgkmcnt(2)
	v_bfe_u32 v3, v6, 16, 1
	ds_read2_b32 v[14:15], v63 offset0:148 offset1:156
	v_lshrrev_b32_e32 v2, 16, v2
	v_add3_u32 v3, v6, v3, s45
	ds_read2_b32 v[16:17], v63 offset0:181 offset1:189
	v_and_or_b32 v2, v3, s56, v2
	s_waitcnt lgkmcnt(3)
	v_bfe_u32 v3, v10, 16, 1
	v_add3_u32 v3, v10, v3, s45
	s_waitcnt lgkmcnt(2)
	v_bfe_u32 v4, v12, 16, 1
	ds_read2_b32 v[18:19], v63 offset0:214 offset1:222
	v_lshrrev_b32_e32 v3, 16, v3
	v_add3_u32 v4, v12, v4, s45
	ds_read2_b32 v[20:21], v63 offset0:247 offset1:255
	v_and_or_b32 v3, v4, s56, v3
	s_waitcnt lgkmcnt(3)
	v_bfe_u32 v4, v14, 16, 1
	v_add3_u32 v4, v14, v4, s45
	s_waitcnt lgkmcnt(2)
	v_bfe_u32 v5, v16, 16, 1
	v_lshrrev_b32_e32 v4, 16, v4
	v_add3_u32 v5, v16, v5, s45
	v_and_or_b32 v4, v5, s56, v4
	s_waitcnt lgkmcnt(1)
	v_bfe_u32 v5, v18, 16, 1
	v_add3_u32 v5, v18, v5, s45
	s_waitcnt lgkmcnt(0)
	v_bfe_u32 v6, v20, 16, 1
	v_lshrrev_b32_e32 v5, 16, v5
	v_add3_u32 v6, v20, v6, s45
	v_and_or_b32 v5, v6, s56, v5
	v_add_u32_e32 v6, 32, v24
	v_and_or_b32 v22, v6, s61, v36
	v_ashrrev_i32_e32 v23, 31, v22
	v_lshlrev_b64 v[22:23], 11, v[22:23]
	v_lshl_add_u64 v[22:23], v[34:35], 0, v[22:23]
	global_store_dwordx4 v[22:23], v[2:5], off sc1
	v_bfe_u32 v6, v21, 16, 1
	v_add3_u32 v6, v21, v6, s45
	v_bfe_u32 v2, v9, 16, 1
	v_add3_u32 v2, v9, v2, s45
	v_bfe_u32 v3, v7, 16, 1
	v_lshrrev_b32_e32 v2, 16, v2
	v_add3_u32 v3, v7, v3, s45
	v_and_or_b32 v2, v3, s56, v2
	v_bfe_u32 v3, v11, 16, 1
	v_add3_u32 v3, v11, v3, s45
	v_bfe_u32 v4, v13, 16, 1
	v_lshrrev_b32_e32 v3, 16, v3
	v_add3_u32 v4, v13, v4, s45
	v_and_or_b32 v3, v4, s56, v3
	v_bfe_u32 v4, v15, 16, 1
	v_add3_u32 v4, v15, v4, s45
	v_bfe_u32 v5, v17, 16, 1
	v_lshrrev_b32_e32 v4, 16, v4
	v_add3_u32 v5, v17, v5, s45
	v_and_or_b32 v4, v5, s56, v4
	v_bfe_u32 v5, v19, 16, 1
	v_add3_u32 v5, v19, v5, s45
	v_lshrrev_b32_e32 v5, 16, v5
	v_and_or_b32 v5, v6, s56, v5
	v_add_u32_e32 v6, 48, v24
	v_and_or_b32 v6, v6, s62, v36
	v_ashrrev_i32_e32 v7, 31, v6
	v_lshlrev_b64 v[6:7], 11, v[6:7]
	v_lshl_add_u64 v[6:7], v[34:35], 0, v[6:7]
	global_store_dwordx4 v[6:7], v[2:5], off sc1
	s_waitcnt lgkmcnt(0)
	s_branch .LBB0_8

.LBB0_41:
	v_ashrrev_i32_e32 v12, 10, v6
	v_and_b32_e32 v11, 0x3ff, v6
	v_ashrrev_i32_e32 v13, 31, v12
	v_mad_u64_u32 v[16:17], s[44:45], v11, s11, v[4:5]
	v_ashrrev_i32_e32 v14, 10, v7
	v_and_b32_e32 v3, 0x3ff, v7
	v_lshl_add_u64 v[12:13], v[12:13], 2, v[16:17]
	v_ashrrev_i32_e32 v15, 31, v14
	v_mad_u64_u32 v[18:19], s[44:45], v3, s11, v[4:5]
	v_add_co_u32_e32 v12, vcc, s13, v12
	v_lshl_add_u64 v[14:15], v[14:15], 2, v[18:19]
	s_nop 0
	v_addc_co_u32_e32 v13, vcc, 0, v13, vcc
	v_lshlrev_b32_e32 v11, 2, v11
	v_add_co_u32_e32 v14, vcc, s13, v14
	v_lshlrev_b32_e32 v3, 2, v3
	global_load_dword v16, v11, s[46:47]
	global_load_dword v17, v3, s[46:47]
	v_addc_co_u32_e32 v15, vcc, 0, v15, vcc
	global_load_dword v12, v[12:13], off
	s_nop 0
	global_load_dword v13, v[14:15], off
	v_add_u32_e32 v10, -2, v10
	v_ashrrev_i32_e32 v19, 31, v6
	v_mov_b32_e32 v18, v6
	v_cmp_eq_u32_e32 vcc, 0, v10
	v_ashrrev_i32_e32 v15, 31, v7
	v_mov_b32_e32 v14, v7
	v_add_u32_e32 v7, s7, v7
	v_add_u32_e32 v6, s3, v6
	v_lshl_add_u64 v[18:19], v[18:19], 1, s[40:41]
	s_or_b64 s[28:29], vcc, s[28:29]
	v_lshl_add_u64 v[14:15], v[14:15], 1, s[40:41]
	s_waitcnt vmcnt(0)
	v_pk_mul_f32 v[12:13], v[12:13], v[16:17]
	s_nop 0
	v_and_b32_sdwa v11, v12, v9 dst_sel:DWORD dst_unused:UNUSED_PAD src0_sel:WORD_1 src1_sel:DWORD
	v_and_b32_sdwa v3, v13, v9 dst_sel:DWORD dst_unused:UNUSED_PAD src0_sel:WORD_1 src1_sel:DWORD
	v_add3_u32 v11, v12, v11, s14
	v_add3_u32 v3, v13, v3, s14
	global_store_short_d16_hi v[18:19], v11, off sc1
	global_store_short_d16_hi v[14:15], v3, off sc1
	s_andn2_b64 exec, exec, s[28:29]
	s_cbranch_execnz .LBB0_41
	s_or_b64 exec, exec, s[28:29]
	v_cmp_ne_u32_e32 vcc, v1, v8
	v_mad_u64_u32 v[2:3], s[14:15], v8, s10, v[2:3]
	s_orn2_b64 s[28:29], vcc, exec

.LBB0_46:
	v_ashrrev_i32_e32 v8, 10, v2
	v_and_b32_e32 v1, 0x3ff, v2
	v_ashrrev_i32_e32 v9, 31, v8
	v_mad_u64_u32 v[10:11], s[14:15], v1, s3, v[6:7]
	v_lshl_add_u64 v[8:9], v[8:9], 2, v[10:11]
	v_add_co_u32_e32 v8, vcc, 0x4000, v8
	v_lshlrev_b32_e32 v1, 2, v1
	s_nop 0
	v_addc_co_u32_e32 v9, vcc, 0, v9, vcc
	global_load_dword v1, v1, s[46:47]
	v_add_u32_e32 v2, s10, v2
	global_load_dword v3, v[8:9], off
	v_cmp_lt_i32_e32 vcc, s11, v2
	s_or_b64 s[18:19], vcc, s[18:19]
	s_waitcnt vmcnt(0)
	v_mul_f32_e32 v1, v3, v1
	v_bfe_u32 v3, v1, 16, 1
	v_add3_u32 v1, v1, v3, s7
	global_store_short_d16_hi v[4:5], v1, off sc1
	v_lshl_add_u64 v[4:5], v[4:5], 0, s[4:5]
	s_andn2_b64 exec, exec, s[18:19]
	s_cbranch_execnz .LBB0_46

.LBB0_49:
	s_or_b64 exec, exec, s[4:5]
	v_mov_b64_e32 v[92:93], v[120:121]
	v_mov_b64_e32 v[94:95], v[122:123]
	v_div_scale_f32 v96, s[4:5], v66, v66, 1.0
	v_div_scale_f32 v98, s[4:5], v82, v82, 1.0
	v_rcp_f32_e32 v104, v96
	v_div_scale_f32 v100, s[6:7], v84, v84, 1.0
	v_rcp_f32_e32 v105, v98
	v_div_scale_f32 v102, s[8:9], v86, v86, 1.0
	v_rcp_f32_e32 v106, v100
	v_rcp_f32_e32 v107, v102
	v_fma_f32 v108, -v96, v104, 1.0
	v_div_scale_f32 v97, vcc, 1.0, v66, 1.0
	v_fma_f32 v109, -v98, v105, 1.0
	v_fmac_f32_e32 v104, v108, v104
	v_div_scale_f32 v99, s[4:5], 1.0, v82, 1.0
	v_fma_f32 v110, -v100, v106, 1.0
	v_fmac_f32_e32 v105, v109, v105
	v_mul_f32_e32 v108, v97, v104
	v_div_scale_f32 v101, s[6:7], 1.0, v84, 1.0
	v_fma_f32 v111, -v102, v107, 1.0
	v_fmac_f32_e32 v106, v110, v106
	v_mul_f32_e32 v109, v99, v105
	v_fma_f32 v112, -v96, v108, v97
	v_div_scale_f32 v103, s[8:9], 1.0, v86, 1.0
	v_fmac_f32_e32 v107, v111, v107
	v_mul_f32_e32 v110, v101, v106
	v_fma_f32 v113, -v98, v109, v99
	v_fmac_f32_e32 v108, v112, v104
	v_mul_f32_e32 v111, v103, v107
	v_fma_f32 v114, -v100, v110, v101
	v_fmac_f32_e32 v109, v113, v105
	v_fma_f32 v96, -v96, v108, v97
	v_fma_f32 v115, -v102, v111, v103
	v_fmac_f32_e32 v110, v114, v106
	v_fma_f32 v97, -v98, v109, v99
	v_div_fmas_f32 v96, v96, v104, v108
	s_mov_b64 vcc, s[4:5]
	v_fmac_f32_e32 v111, v115, v107
	v_fma_f32 v98, -v100, v110, v101
	v_div_fixup_f32 v66, v96, v66, 1.0
	v_div_fmas_f32 v96, v97, v105, v109
	s_mov_b64 vcc, s[6:7]
	v_fma_f32 v99, -v102, v111, v103
	v_div_fixup_f32 v82, v96, v82, 1.0
	v_div_fmas_f32 v96, v98, v106, v110
	s_mov_b64 vcc, s[8:9]
	v_div_fixup_f32 v84, v96, v84, 1.0
	v_div_fmas_f32 v96, v99, v107, v111
	v_div_fixup_f32 v86, v96, v86, 1.0
	v_pk_mul_f32 v[58:59], v[58:59], v[86:87] op_sel_hi:[1,0]
	v_pk_mul_f32 v[60:61], v[60:61], v[86:87] op_sel_hi:[1,0]
	v_lshl_add_u64 v[80:81], s[52:53], 0, v[72:73]
	v_pk_mul_f32 v[62:63], v[62:63], v[84:85] op_sel_hi:[1,0]
	v_add_co_u32_e64 v80, s[10:11], s63, v80
	v_pk_mul_f32 v[64:65], v[64:65], v[84:85] op_sel_hi:[1,0]
	s_nop 0
	v_addc_co_u32_e64 v81, s[10:11], 0, v81, s[10:11]
	v_pk_mul_f32 v[54:55], v[54:55], v[82:83] op_sel_hi:[1,0]
	v_pk_mul_f32 v[56:57], v[56:57], v[82:83] op_sel_hi:[1,0]
	v_pk_mul_f32 v[50:51], v[50:51], v[66:67] op_sel_hi:[1,0]
	v_pk_mul_f32 v[52:53], v[52:53], v[66:67] op_sel_hi:[1,0]
	v_pk_mul_f32 v[38:39], v[38:39], v[86:87] op_sel_hi:[1,0]
	v_pk_mul_f32 v[40:41], v[40:41], v[86:87] op_sel_hi:[1,0]
	v_pk_mul_f32 v[42:43], v[42:43], v[84:85] op_sel_hi:[1,0]
	v_pk_mul_f32 v[44:45], v[44:45], v[84:85] op_sel_hi:[1,0]
	v_pk_mul_f32 v[46:47], v[46:47], v[82:83] op_sel_hi:[1,0]
	v_pk_mul_f32 v[48:49], v[48:49], v[82:83] op_sel_hi:[1,0]
	v_pk_mul_f32 v[34:35], v[34:35], v[66:67] op_sel_hi:[1,0]
	v_pk_mul_f32 v[36:37], v[36:37], v[66:67] op_sel_hi:[1,0]
	v_pk_mul_f32 v[18:19], v[18:19], v[86:87] op_sel_hi:[1,0]
	v_pk_mul_f32 v[20:21], v[20:21], v[86:87] op_sel_hi:[1,0]
	v_pk_mul_f32 v[30:31], v[30:31], v[66:67] op_sel_hi:[1,0]
	v_pk_mul_f32 v[60:61], v[60:61], v[94:95]
	v_pk_mul_f32 v[58:59], v[58:59], v[92:93]
	v_bfe_u32 v98, v60, 16, 1
	v_bfe_u32 v96, v58, 16, 1
	v_bfe_u32 v97, v59, 16, 1
	v_bfe_u32 v99, v61, 16, 1
	v_add3_u32 v58, v58, v96, s19
	v_add3_u32 v60, v60, v98, s19
	v_pk_mul_f32 v[62:63], v[62:63], v[92:93]
	v_add3_u32 v59, v59, v97, s19
	v_add3_u32 v61, v61, v99, s19
	v_lshrrev_b32_e32 v58, 16, v58
	v_lshrrev_b32_e32 v60, 16, v60
	v_bfe_u32 v100, v62, 16, 1
	v_and_or_b32 v58, v59, s62, v58
	v_and_or_b32 v59, v61, s62, v60
	v_add3_u32 v62, v62, v100, s19
	global_store_dwordx2 v[80:81], v[58:59], off sc1
	v_bfe_u32 v58, v63, 16, 1
	v_pk_mul_f32 v[64:65], v[64:65], v[94:95]
	v_lshrrev_b32_e32 v62, 16, v62
	v_add3_u32 v58, v63, v58, s19
	v_and_or_b32 v60, v58, s62, v62
	v_bfe_u32 v58, v64, 16, 1
	v_add3_u32 v58, v64, v58, s19
	v_bfe_u32 v59, v65, 16, 1
	v_lshrrev_b32_e32 v58, 16, v58
	v_add3_u32 v59, v65, v59, s19
	v_and_or_b32 v61, v59, s62, v58
	v_lshl_add_u64 v[58:59], s[52:53], 0, v[74:75]
	v_pk_mul_f32 v[54:55], v[54:55], v[92:93]
	global_store_dwordx2 v[58:59], v[60:61], off offset:-1024 sc1
	v_bfe_u32 v60, v54, 16, 1
	v_add3_u32 v54, v54, v60, s19
	v_bfe_u32 v60, v55, 16, 1
	v_pk_mul_f32 v[56:57], v[56:57], v[94:95]
	v_lshrrev_b32_e32 v54, 16, v54
	v_add3_u32 v55, v55, v60, s19
	v_and_or_b32 v60, v55, s62, v54
	v_bfe_u32 v54, v56, 16, 1
	v_pk_mul_f32 v[50:51], v[50:51], v[92:93]
	v_add3_u32 v54, v56, v54, s19
	v_bfe_u32 v56, v50, 16, 1
	v_add3_u32 v50, v50, v56, s19
	v_bfe_u32 v56, v51, 16, 1
	v_pk_mul_f32 v[52:53], v[52:53], v[94:95]
	v_lshrrev_b32_e32 v50, 16, v50
	v_add3_u32 v51, v51, v56, s19
	v_and_or_b32 v56, v51, s62, v50
	v_bfe_u32 v50, v52, 16, 1
	v_bfe_u32 v55, v57, 16, 1
	v_add3_u32 v50, v52, v50, s19
	v_bfe_u32 v51, v53, 16, 1
	v_lshrrev_b32_e32 v54, 16, v54
	v_add3_u32 v55, v57, v55, s19
	v_lshrrev_b32_e32 v50, 16, v50
	v_add3_u32 v51, v53, v51, s19
	v_and_or_b32 v61, v55, s62, v54
	v_lshl_add_u64 v[54:55], s[52:53], 0, v[76:77]
	v_and_or_b32 v57, v51, s62, v50
	v_lshl_add_u64 v[50:51], s[52:53], 0, v[78:79]
	global_store_dwordx2 v[54:55], v[60:61], off offset:-1024 sc1
	global_store_dwordx2 v[50:51], v[56:57], off offset:-1024 sc1
	s_nop 1
	v_mov_b64_e32 v[60:61], v[124:125]
	v_mov_b64_e32 v[62:63], v[126:127]
	v_pk_mul_f32 v[32:33], v[32:33], v[66:67] op_sel_hi:[1,0]
	v_pk_mul_f32 v[26:27], v[26:27], v[82:83] op_sel_hi:[1,0]
	v_pk_mul_f32 v[28:29], v[28:29], v[82:83] op_sel_hi:[1,0]
	v_pk_mul_f32 v[22:23], v[22:23], v[84:85] op_sel_hi:[1,0]
	v_pk_mul_f32 v[24:25], v[24:25], v[84:85] op_sel_hi:[1,0]
	s_add_i32 s12, s12, s18
	s_add_u32 s46, s46, s28
	s_addc_u32 s47, s47, s29
	s_add_u32 s48, s48, s28
	v_pk_mul_f32 v[2:3], v[2:3], v[86:87] op_sel_hi:[1,0]
	v_pk_mul_f32 v[4:5], v[4:5], v[86:87] op_sel_hi:[1,0]
	s_addc_u32 s49, s49, s29
	v_pk_mul_f32 v[14:15], v[14:15], v[66:67] op_sel_hi:[1,0]
	v_pk_mul_f32 v[16:17], v[16:17], v[66:67] op_sel_hi:[1,0]
	v_pk_mul_f32 v[10:11], v[10:11], v[82:83] op_sel_hi:[1,0]
	v_pk_mul_f32 v[12:13], v[12:13], v[82:83] op_sel_hi:[1,0]
	v_pk_mul_f32 v[6:7], v[6:7], v[84:85] op_sel_hi:[1,0]
	v_pk_mul_f32 v[8:9], v[8:9], v[84:85] op_sel_hi:[1,0]
	s_add_u32 s56, s56, s28
	s_addc_u32 s57, s57, s29
	s_add_u32 s60, s60, s28
	s_addc_u32 s61, s61, s29
	v_lshl_add_u64 v[70:71], v[70:71], 0, s[36:37]
	v_lshl_add_u64 v[72:73], v[72:73], 0, s[44:45]
	v_lshl_add_u64 v[74:75], v[74:75], 0, s[44:45]
	v_lshl_add_u64 v[76:77], v[76:77], 0, s[44:45]
	s_cmpk_gt_i32 s12, 0x3fff
	v_lshl_add_u64 v[78:79], v[78:79], 0, s[44:45]
	v_pk_mul_f32 v[40:41], v[40:41], v[62:63]
	v_pk_mul_f32 v[38:39], v[38:39], v[60:61]
	v_pk_mul_f32 v[44:45], v[44:45], v[62:63]
	v_pk_mul_f32 v[42:43], v[42:43], v[60:61]
	v_bfe_u32 v52, v38, 16, 1
	v_bfe_u32 v56, v40, 16, 1
	v_bfe_u32 v53, v39, 16, 1
	v_bfe_u32 v57, v41, 16, 1
	v_bfe_u32 v64, v42, 16, 1
	v_bfe_u32 v92, v44, 16, 1
	v_add3_u32 v38, v38, v52, s19
	v_add3_u32 v40, v40, v56, s19
	v_bfe_u32 v65, v43, 16, 1
	v_bfe_u32 v93, v45, 16, 1
	v_add3_u32 v39, v39, v53, s19
	v_add3_u32 v41, v41, v57, s19
	v_add3_u32 v42, v42, v64, s19
	v_add3_u32 v44, v44, v92, s19
	v_lshrrev_b32_e32 v38, 16, v38
	v_lshrrev_b32_e32 v40, 16, v40
	v_pk_mul_f32 v[46:47], v[46:47], v[60:61]
	v_add3_u32 v43, v43, v65, s19
	v_add3_u32 v45, v45, v93, s19
	v_lshrrev_b32_e32 v42, 16, v42
	v_lshrrev_b32_e32 v44, 16, v44
	v_and_or_b32 v38, v39, s62, v38
	v_and_or_b32 v39, v41, s62, v40
	v_and_or_b32 v40, v43, s62, v42
	v_and_or_b32 v41, v45, s62, v44
	global_store_dwordx2 v[80:81], v[38:39], off offset:512 sc1
	global_store_dwordx2 v[58:59], v[40:41], off offset:-512 sc1
	v_bfe_u32 v38, v46, 16, 1
	v_add3_u32 v38, v46, v38, s19
	v_bfe_u32 v39, v47, 16, 1
	v_pk_mul_f32 v[48:49], v[48:49], v[62:63]
	v_lshrrev_b32_e32 v38, 16, v38
	v_add3_u32 v39, v47, v39, s19
	v_and_or_b32 v38, v39, s62, v38
	v_bfe_u32 v39, v48, 16, 1
	v_add3_u32 v39, v48, v39, s19
	v_bfe_u32 v40, v49, 16, 1
	v_lshrrev_b32_e32 v39, 16, v39
	v_add3_u32 v40, v49, v40, s19
	v_and_or_b32 v39, v40, s62, v39
	v_pk_mul_f32 v[34:35], v[34:35], v[60:61]
	global_store_dwordx2 v[54:55], v[38:39], off offset:-512 sc1
	v_bfe_u32 v38, v34, 16, 1
	v_add3_u32 v34, v34, v38, s19
	v_bfe_u32 v38, v35, 16, 1
	v_pk_mul_f32 v[36:37], v[36:37], v[62:63]
	v_lshrrev_b32_e32 v34, 16, v34
	v_add3_u32 v35, v35, v38, s19
	v_and_or_b32 v34, v35, s62, v34
	v_bfe_u32 v35, v36, 16, 1
	v_add3_u32 v35, v36, v35, s19
	v_bfe_u32 v36, v37, 16, 1
	v_lshrrev_b32_e32 v35, 16, v35
	v_add3_u32 v36, v37, v36, s19
	v_and_or_b32 v35, v36, s62, v35
	global_store_dwordx2 v[50:51], v[34:35], off offset:-512 sc1
	s_nop 1
	v_mov_b64_e32 v[34:35], v[128:129]
	v_mov_b64_e32 v[36:37], v[130:131]
	v_pk_mul_f32 v[20:21], v[20:21], v[36:37]
	v_pk_mul_f32 v[18:19], v[18:19], v[34:35]
	v_pk_mul_f32 v[24:25], v[24:25], v[36:37]
	v_pk_mul_f32 v[22:23], v[22:23], v[34:35]
	v_pk_mul_f32 v[28:29], v[28:29], v[36:37]
	v_pk_mul_f32 v[26:27], v[26:27], v[34:35]
	v_pk_mul_f32 v[32:33], v[32:33], v[36:37]
	v_pk_mul_f32 v[30:31], v[30:31], v[34:35]
	v_bfe_u32 v34, v18, 16, 1
	v_bfe_u32 v36, v20, 16, 1
	v_bfe_u32 v35, v19, 16, 1
	v_bfe_u32 v37, v21, 16, 1
	v_bfe_u32 v38, v22, 16, 1
	v_bfe_u32 v40, v24, 16, 1
	v_bfe_u32 v42, v26, 16, 1
	v_bfe_u32 v44, v28, 16, 1
	v_add3_u32 v18, v18, v34, s19
	v_add3_u32 v20, v20, v36, s19
	v_bfe_u32 v39, v23, 16, 1
	v_bfe_u32 v41, v25, 16, 1
	v_bfe_u32 v43, v27, 16, 1
	v_bfe_u32 v45, v29, 16, 1
	v_add3_u32 v19, v19, v35, s19
	v_add3_u32 v21, v21, v37, s19
	v_add3_u32 v22, v22, v38, s19
	v_add3_u32 v24, v24, v40, s19
	v_add3_u32 v26, v26, v42, s19
	v_add3_u32 v28, v28, v44, s19
	v_lshrrev_b32_e32 v18, 16, v18
	v_lshrrev_b32_e32 v20, 16, v20
	v_add3_u32 v23, v23, v39, s19
	v_add3_u32 v25, v25, v41, s19
	v_add3_u32 v27, v27, v43, s19
	v_add3_u32 v29, v29, v45, s19
	v_lshrrev_b32_e32 v22, 16, v22
	v_lshrrev_b32_e32 v24, 16, v24
	v_lshrrev_b32_e32 v26, 16, v26
	v_lshrrev_b32_e32 v28, 16, v28
	v_and_or_b32 v18, v19, s62, v18
	v_and_or_b32 v19, v21, s62, v20
	v_and_or_b32 v20, v23, s62, v22
	v_and_or_b32 v21, v25, s62, v24
	v_and_or_b32 v22, v27, s62, v26
	v_and_or_b32 v23, v29, s62, v28
	global_store_dwordx2 v[80:81], v[18:19], off offset:1024 sc1
	global_store_dwordx2 v[58:59], v[20:21], off sc1
	global_store_dwordx2 v[54:55], v[22:23], off sc1
	v_bfe_u32 v18, v30, 16, 1
	v_add3_u32 v18, v30, v18, s19
	v_bfe_u32 v19, v31, 16, 1
	v_lshrrev_b32_e32 v18, 16, v18
	v_add3_u32 v19, v31, v19, s19
	v_and_or_b32 v18, v19, s62, v18
	v_bfe_u32 v19, v32, 16, 1
	v_add3_u32 v19, v32, v19, s19
	v_bfe_u32 v20, v33, 16, 1
	v_lshrrev_b32_e32 v19, 16, v19
	v_add3_u32 v20, v33, v20, s19
	v_and_or_b32 v19, v20, s62, v19
	global_store_dwordx2 v[50:51], v[18:19], off sc1
	s_nop 1
	v_mov_b64_e32 v[18:19], v[132:133]
	v_mov_b64_e32 v[20:21], v[134:135]
	v_pk_mul_f32 v[4:5], v[4:5], v[20:21]
	v_pk_mul_f32 v[2:3], v[2:3], v[18:19]
	v_pk_mul_f32 v[8:9], v[8:9], v[20:21]
	v_pk_mul_f32 v[6:7], v[6:7], v[18:19]
	v_pk_mul_f32 v[12:13], v[12:13], v[20:21]
	v_pk_mul_f32 v[10:11], v[10:11], v[18:19]
	v_pk_mul_f32 v[16:17], v[16:17], v[20:21]
	v_pk_mul_f32 v[14:15], v[14:15], v[18:19]
	v_bfe_u32 v18, v2, 16, 1
	v_bfe_u32 v20, v4, 16, 1
	v_bfe_u32 v19, v3, 16, 1
	v_bfe_u32 v21, v5, 16, 1
	v_bfe_u32 v22, v6, 16, 1
	v_bfe_u32 v24, v8, 16, 1
	v_bfe_u32 v26, v10, 16, 1
	v_bfe_u32 v28, v12, 16, 1
	v_bfe_u32 v30, v14, 16, 1
	v_bfe_u32 v32, v16, 16, 1
	v_add3_u32 v2, v2, v18, s19
	v_add3_u32 v4, v4, v20, s19
	v_bfe_u32 v23, v7, 16, 1
	v_bfe_u32 v25, v9, 16, 1
	v_bfe_u32 v27, v11, 16, 1
	v_bfe_u32 v29, v13, 16, 1
	v_bfe_u32 v31, v15, 16, 1
	v_bfe_u32 v33, v17, 16, 1
	v_add3_u32 v3, v3, v19, s19
	v_add3_u32 v5, v5, v21, s19
	v_add3_u32 v6, v6, v22, s19
	v_add3_u32 v8, v8, v24, s19
	v_add3_u32 v10, v10, v26, s19
	v_add3_u32 v12, v12, v28, s19
	v_add3_u32 v14, v14, v30, s19
	v_add3_u32 v16, v16, v32, s19
	v_lshrrev_b32_e32 v2, 16, v2
	v_lshrrev_b32_e32 v4, 16, v4
	v_add3_u32 v7, v7, v23, s19
	v_add3_u32 v9, v9, v25, s19
	v_add3_u32 v11, v11, v27, s19
	v_add3_u32 v13, v13, v29, s19
	v_add3_u32 v15, v15, v31, s19
	v_add3_u32 v17, v17, v33, s19
	v_lshrrev_b32_e32 v6, 16, v6
	v_lshrrev_b32_e32 v8, 16, v8
	v_lshrrev_b32_e32 v10, 16, v10
	v_lshrrev_b32_e32 v12, 16, v12
	v_lshrrev_b32_e32 v14, 16, v14
	v_lshrrev_b32_e32 v16, 16, v16
	v_and_or_b32 v2, v3, s62, v2
	v_and_or_b32 v3, v5, s62, v4
	v_and_or_b32 v4, v7, s62, v6
	v_and_or_b32 v5, v9, s62, v8
	v_and_or_b32 v6, v11, s62, v10
	v_and_or_b32 v7, v13, s62, v12
	v_and_or_b32 v8, v15, s62, v14
	v_and_or_b32 v9, v17, s62, v16
	global_store_dwordx2 v[80:81], v[2:3], off offset:1536 sc1
	global_store_dwordx2 v[58:59], v[4:5], off offset:512 sc1
	global_store_dwordx2 v[54:55], v[6:7], off offset:512 sc1
	global_store_dwordx2 v[50:51], v[8:9], off offset:512 sc1
	s_cbranch_scc1 .LBB0_58
.LBB0_50:
	global_load_dwordx4 v[58:61], v[70:71], off nt
	global_load_dwordx4 v[38:41], v[70:71], off offset:1024 nt
	global_load_dwordx4 v[18:21], v[70:71], off offset:2048 nt
	global_load_dwordx4 v[2:5], v[70:71], off offset:3072 nt
	v_lshl_add_u64 v[10:11], v[70:71], 0, s[20:21]
	v_lshl_add_u64 v[14:15], v[10:11], 0, s[20:21]
	global_load_dwordx4 v[62:65], v[10:11], off nt
	global_load_dwordx4 v[42:45], v[10:11], off offset:1024 nt
	global_load_dwordx4 v[22:25], v[10:11], off offset:2048 nt
	global_load_dwordx4 v[6:9], v[10:11], off offset:3072 nt
	global_load_dwordx4 v[54:57], v[14:15], off nt
	global_load_dwordx4 v[46:49], v[14:15], off offset:1024 nt
	global_load_dwordx4 v[26:29], v[14:15], off offset:2048 nt
	s_nop 0
	global_load_dwordx4 v[10:13], v[14:15], off offset:3072 nt
	v_lshl_add_u64 v[14:15], v[14:15], 0, s[20:21]
	global_load_dwordx4 v[50:53], v[14:15], off nt
	global_load_dwordx4 v[34:37], v[14:15], off offset:1024 nt
	global_load_dwordx4 v[30:33], v[14:15], off offset:2048 nt
	s_nop 0
	global_load_dwordx4 v[14:17], v[14:15], off offset:3072 nt
	s_waitcnt vmcnt(15)
	v_mul_f32_e32 v66, v59, v59
	v_mul_f32_e32 v80, v61, v61
	s_waitcnt vmcnt(14)
	v_mul_f32_e32 v81, v39, v39
	v_mul_f32_e32 v82, v41, v41
	s_waitcnt vmcnt(13)
	v_mul_f32_e32 v84, v19, v19
	v_mul_f32_e32 v86, v21, v21
	v_fmac_f32_e32 v66, v58, v58
	v_fmac_f32_e32 v80, v60, v60
	v_fmac_f32_e32 v81, v38, v38
	v_fmac_f32_e32 v82, v40, v40
	s_waitcnt vmcnt(12)
	v_mul_f32_e32 v92, v3, v3
	v_mul_f32_e32 v93, v5, v5
	v_fmac_f32_e32 v84, v18, v18
	v_fmac_f32_e32 v86, v20, v20
	v_add_f32_e32 v66, v66, v80
	v_add_f32_e32 v80, v81, v82
	v_fmac_f32_e32 v92, v2, v2
	v_fmac_f32_e32 v93, v4, v4
	v_add_f32_e32 v81, v84, v86
	v_add_f32_e32 v66, v66, v80
	v_add_f32_e32 v82, v92, v93
	v_add_f32_e32 v66, v66, v81
	v_add_f32_e32 v66, v66, v82
	s_nop 1
	v_add_f32_dpp v66, v66, v66 row_ror:8 row_mask:0xf bank_mask:0xf
	s_nop 1
	v_add_f32_dpp v66, v66, v66 row_ror:4 row_mask:0xf bank_mask:0xf
	s_nop 1
	v_add_f32_dpp v66, v66, v66 row_ror:2 row_mask:0xf bank_mask:0xf
	s_nop 1
	v_add_f32_dpp v66, v66, v66 row_ror:1 row_mask:0xf bank_mask:0xf
	s_nop 1
	v_add_f32_dpp v66, v66, v66 row_bcast:15 row_mask:0xa bank_mask:0xf
	s_nop 1
	v_add_f32_dpp v66, v66, v66 row_bcast:31 row_mask:0xc bank_mask:0xf
	s_nop 1
	v_readlane_b32 s4, v66, 63
	s_nop 1
	v_mov_b32_e32 v66, s4
	v_fmamk_f32 v66, v66, 0x3a800000, v90
	v_mul_f32_e32 v80, 0x4f800000, v66
	v_cmp_gt_f32_e32 vcc, s13, v66
	s_nop 1
	v_cndmask_b32_e32 v66, v66, v80, vcc
	v_sqrt_f32_e32 v80, v66
	s_nop 0
	v_add_u32_e32 v81, -1, v80
	v_add_u32_e32 v82, 1, v80
	v_fma_f32 v84, -v81, v80, v66
	v_fma_f32 v86, -v82, v80, v66
	v_cmp_ge_f32_e64 s[4:5], 0, v84
	s_nop 1
	v_cndmask_b32_e64 v80, v80, v81, s[4:5]
	v_cmp_lt_f32_e64 s[4:5], 0, v86
	s_nop 1
	v_cndmask_b32_e64 v80, v80, v82, s[4:5]
	v_mul_f32_e32 v81, 0x37800000, v80
	v_cndmask_b32_e32 v80, v80, v81, vcc
	v_cmp_class_f32_e32 vcc, v66, v91
	s_nop 1
	v_cndmask_b32_e32 v86, v80, v66, vcc
	s_and_saveexec_b64 s[4:5], s[0:1]
	s_cbranch_execz .LBB0_52
	s_add_u32 s6, s52, s46
	s_addc_u32 s7, s53, s47
	global_store_dword v67, v86, s[6:7] sc1
.LBB0_52:
	s_or_b64 exec, exec, s[4:5]
	s_waitcnt vmcnt(11)
	v_mul_f32_e32 v66, v63, v63
	v_mul_f32_e32 v80, v65, v65
	v_fmac_f32_e32 v66, v62, v62
	v_fmac_f32_e32 v80, v64, v64
	v_add_f32_e32 v66, v66, v80
	s_waitcnt vmcnt(10)
	v_mul_f32_e32 v80, v43, v43
	v_mul_f32_e32 v81, v45, v45
	v_fmac_f32_e32 v80, v42, v42
	v_fmac_f32_e32 v81, v44, v44
	v_add_f32_e32 v80, v80, v81
	v_add_f32_e32 v66, v66, v80
	s_waitcnt vmcnt(9)
	v_mul_f32_e32 v80, v23, v23
	v_mul_f32_e32 v81, v25, v25
	v_fmac_f32_e32 v80, v22, v22
	v_fmac_f32_e32 v81, v24, v24
	v_add_f32_e32 v80, v80, v81
	v_add_f32_e32 v66, v66, v80
	s_waitcnt vmcnt(8)
	v_mul_f32_e32 v80, v7, v7
	v_mul_f32_e32 v81, v9, v9
	v_fmac_f32_e32 v80, v6, v6
	v_fmac_f32_e32 v81, v8, v8
	v_add_f32_e32 v80, v80, v81
	v_add_f32_e32 v66, v66, v80
	s_nop 1
	v_add_f32_dpp v66, v66, v66 row_ror:8 row_mask:0xf bank_mask:0xf
	s_nop 1
	v_add_f32_dpp v66, v66, v66 row_ror:4 row_mask:0xf bank_mask:0xf
	s_nop 1
	v_add_f32_dpp v66, v66, v66 row_ror:2 row_mask:0xf bank_mask:0xf
	s_nop 1
	v_add_f32_dpp v66, v66, v66 row_ror:1 row_mask:0xf bank_mask:0xf
	s_nop 1
	v_add_f32_dpp v66, v66, v66 row_bcast:15 row_mask:0xa bank_mask:0xf
	s_nop 1
	v_add_f32_dpp v66, v66, v66 row_bcast:31 row_mask:0xc bank_mask:0xf
	s_nop 1
	v_readlane_b32 s4, v66, 63
	s_nop 1
	v_mov_b32_e32 v66, s4
	v_fmamk_f32 v66, v66, 0x3a800000, v90
	v_mul_f32_e32 v80, 0x4f800000, v66
	v_cmp_gt_f32_e32 vcc, s13, v66
	s_nop 1
	v_cndmask_b32_e32 v66, v66, v80, vcc
	v_sqrt_f32_e32 v80, v66
	s_nop 0
	v_add_u32_e32 v81, -1, v80
	v_add_u32_e32 v82, 1, v80
	v_fma_f32 v84, -v81, v80, v66
	v_fma_f32 v92, -v82, v80, v66
	v_cmp_ge_f32_e64 s[4:5], 0, v84
	s_nop 1
	v_cndmask_b32_e64 v80, v80, v81, s[4:5]
	v_cmp_lt_f32_e64 s[4:5], 0, v92
	s_nop 1
	v_cndmask_b32_e64 v80, v80, v82, s[4:5]
	v_mul_f32_e32 v81, 0x37800000, v80
	v_cndmask_b32_e32 v80, v80, v81, vcc
	v_cmp_class_f32_e32 vcc, v66, v91
	s_nop 1
	v_cndmask_b32_e32 v84, v80, v66, vcc
	s_and_saveexec_b64 s[4:5], s[0:1]
	s_cbranch_execz .LBB0_54
	s_add_u32 s6, s52, s48
	s_addc_u32 s7, s53, s49
	global_store_dword v67, v84, s[6:7] sc1
.LBB0_54:
	s_or_b64 exec, exec, s[4:5]
	s_waitcnt vmcnt(7)
	v_mul_f32_e32 v66, v55, v55
	v_mul_f32_e32 v80, v57, v57
	v_fmac_f32_e32 v66, v54, v54
	v_fmac_f32_e32 v80, v56, v56
	v_add_f32_e32 v66, v66, v80
	s_waitcnt vmcnt(6)
	v_mul_f32_e32 v80, v47, v47
	v_mul_f32_e32 v81, v49, v49
	v_fmac_f32_e32 v80, v46, v46
	v_fmac_f32_e32 v81, v48, v48
	v_add_f32_e32 v80, v80, v81
	v_add_f32_e32 v66, v66, v80
	s_waitcnt vmcnt(5)
	v_mul_f32_e32 v80, v27, v27
	v_mul_f32_e32 v81, v29, v29
	v_fmac_f32_e32 v80, v26, v26
	v_fmac_f32_e32 v81, v28, v28
	v_add_f32_e32 v80, v80, v81
	v_add_f32_e32 v66, v66, v80
	s_waitcnt vmcnt(4)
	v_mul_f32_e32 v80, v11, v11
	v_mul_f32_e32 v81, v13, v13
	v_fmac_f32_e32 v80, v10, v10
	v_fmac_f32_e32 v81, v12, v12
	v_add_f32_e32 v80, v80, v81
	v_add_f32_e32 v66, v66, v80
	s_nop 1
	v_add_f32_dpp v66, v66, v66 row_ror:8 row_mask:0xf bank_mask:0xf
	s_nop 1
	v_add_f32_dpp v66, v66, v66 row_ror:4 row_mask:0xf bank_mask:0xf
	s_nop 1
	v_add_f32_dpp v66, v66, v66 row_ror:2 row_mask:0xf bank_mask:0xf
	s_nop 1
	v_add_f32_dpp v66, v66, v66 row_ror:1 row_mask:0xf bank_mask:0xf
	s_nop 1
	v_add_f32_dpp v66, v66, v66 row_bcast:15 row_mask:0xa bank_mask:0xf
	s_nop 1
	v_add_f32_dpp v66, v66, v66 row_bcast:31 row_mask:0xc bank_mask:0xf
	s_nop 1
	v_readlane_b32 s4, v66, 63
	s_nop 1
	v_mov_b32_e32 v66, s4
	v_fmamk_f32 v66, v66, 0x3a800000, v90
	v_mul_f32_e32 v80, 0x4f800000, v66
	v_cmp_gt_f32_e32 vcc, s13, v66
	s_nop 1
	v_cndmask_b32_e32 v66, v66, v80, vcc
	v_sqrt_f32_e32 v80, v66
	s_nop 0
	v_add_u32_e32 v81, -1, v80
	v_add_u32_e32 v82, 1, v80
	v_fma_f32 v92, -v81, v80, v66
	v_fma_f32 v93, -v82, v80, v66
	v_cmp_ge_f32_e64 s[4:5], 0, v92
	s_nop 1
	v_cndmask_b32_e64 v80, v80, v81, s[4:5]
	v_cmp_lt_f32_e64 s[4:5], 0, v93
	s_nop 1
	v_cndmask_b32_e64 v80, v80, v82, s[4:5]
	v_mul_f32_e32 v81, 0x37800000, v80
	v_cndmask_b32_e32 v80, v80, v81, vcc
	v_cmp_class_f32_e32 vcc, v66, v91
	s_nop 1
	v_cndmask_b32_e32 v82, v80, v66, vcc
	s_and_saveexec_b64 s[4:5], s[0:1]
	s_cbranch_execz .LBB0_56
	s_add_u32 s6, s52, s56
	s_addc_u32 s7, s53, s57
	global_store_dword v67, v82, s[6:7] sc1
.LBB0_56:
	s_or_b64 exec, exec, s[4:5]
	s_waitcnt vmcnt(3)
	v_mul_f32_e32 v66, v51, v51
	v_mul_f32_e32 v80, v53, v53
	v_fmac_f32_e32 v66, v50, v50
	v_fmac_f32_e32 v80, v52, v52
	v_add_f32_e32 v66, v66, v80
	s_waitcnt vmcnt(2)
	v_mul_f32_e32 v80, v35, v35
	v_mul_f32_e32 v81, v37, v37
	v_fmac_f32_e32 v80, v34, v34
	v_fmac_f32_e32 v81, v36, v36
	v_add_f32_e32 v80, v80, v81
	v_add_f32_e32 v66, v66, v80
	s_waitcnt vmcnt(1)
	v_mul_f32_e32 v80, v31, v31
	v_mul_f32_e32 v81, v33, v33
	v_fmac_f32_e32 v80, v30, v30
	v_fmac_f32_e32 v81, v32, v32
	v_add_f32_e32 v80, v80, v81
	v_add_f32_e32 v66, v66, v80
	s_waitcnt vmcnt(0)
	v_mul_f32_e32 v80, v15, v15
	v_mul_f32_e32 v81, v17, v17
	v_fmac_f32_e32 v80, v14, v14
	v_fmac_f32_e32 v81, v16, v16
	v_add_f32_e32 v80, v80, v81
	v_add_f32_e32 v66, v66, v80
	s_nop 1
	v_add_f32_dpp v66, v66, v66 row_ror:8 row_mask:0xf bank_mask:0xf
	s_nop 1
	v_add_f32_dpp v66, v66, v66 row_ror:4 row_mask:0xf bank_mask:0xf
	s_nop 1
	v_add_f32_dpp v66, v66, v66 row_ror:2 row_mask:0xf bank_mask:0xf
	s_nop 1
	v_add_f32_dpp v66, v66, v66 row_ror:1 row_mask:0xf bank_mask:0xf
	s_nop 1
	v_add_f32_dpp v66, v66, v66 row_bcast:15 row_mask:0xa bank_mask:0xf
	s_nop 1
	v_add_f32_dpp v66, v66, v66 row_bcast:31 row_mask:0xc bank_mask:0xf
	s_nop 1
	v_readlane_b32 s4, v66, 63
	s_nop 1
	v_mov_b32_e32 v66, s4
	v_fmamk_f32 v66, v66, 0x3a800000, v90
	v_mul_f32_e32 v80, 0x4f800000, v66
	v_cmp_gt_f32_e32 vcc, s13, v66
	s_nop 1
	v_cndmask_b32_e32 v66, v66, v80, vcc
	v_sqrt_f32_e32 v80, v66
	s_nop 0
	v_add_u32_e32 v81, -1, v80
	v_add_u32_e32 v92, 1, v80
	v_fma_f32 v93, -v81, v80, v66
	v_fma_f32 v94, -v92, v80, v66
	v_cmp_ge_f32_e64 s[4:5], 0, v93
	s_nop 1
	v_cndmask_b32_e64 v80, v80, v81, s[4:5]
	v_cmp_lt_f32_e64 s[4:5], 0, v94
	s_nop 1
	v_cndmask_b32_e64 v80, v80, v92, s[4:5]
	v_mul_f32_e32 v81, 0x37800000, v80
	v_cndmask_b32_e32 v80, v80, v81, vcc
	v_cmp_class_f32_e32 vcc, v66, v91
	s_nop 1
	v_cndmask_b32_e32 v66, v80, v66, vcc
	s_and_saveexec_b64 s[4:5], s[0:1]
	s_cbranch_execz .LBB0_49
	s_add_u32 s6, s52, s60
	s_addc_u32 s7, s53, s61
	global_store_dword v67, v66, s[6:7] sc1
	s_branch .LBB0_49

.LBB0_90:
	s_or_b64 exec, exec, s[8:9]
	v_cvt_f32_u32_e32 v4, v2
	s_waitcnt vmcnt(0)
	v_readfirstlane_b32 s3, v3
	v_sub_u32_e32 v3, 0, v2
	v_rcp_iflag_f32_e32 v4, v4
	v_add_u32_e32 v5, s3, v1
	v_mul_f32_e32 v4, 0x4f7ffffe, v4
	v_cvt_u32_f32_e32 v4, v4
	v_mul_lo_u32 v1, v3, v4
	v_mul_hi_u32 v1, v4, v1
	v_add_u32_e32 v1, v4, v1
	v_mul_hi_u32 v1, v5, v1
	v_mul_lo_u32 v3, v1, v2
	v_sub_u32_e32 v3, v5, v3
	v_add_u32_e32 v4, 1, v1
	v_cmp_ge_u32_e32 vcc, v3, v2
	s_nop 1
	v_cndmask_b32_e32 v1, v1, v4, vcc
	v_sub_u32_e32 v4, v3, v2
	v_cndmask_b32_e32 v3, v3, v4, vcc
	v_add_u32_e32 v4, 1, v1
	v_cmp_ge_u32_e32 vcc, v3, v2
	v_add_u32_e32 v3, 1, v5
	s_nop 0
	v_cndmask_b32_e32 v1, v1, v4, vcc
	v_mul_lo_u32 v4, v2, v1
	v_add_u32_e32 v2, v4, v2
	v_cmp_ne_u32_e32 vcc, v3, v2
	s_cbranch_vccnz .Lmy_ft1_nl
	s_waitcnt vmcnt(0) lgkmcnt(0)
	v_mov_b32_e32 v2, 0x3000
	v_mov_b32_e32 v3, 1
	global_atomic_add v2, v3, s[52:53] offset:1024
